# v2 (bb/cc load hoist + W1 b128 reads in ssm_build) plus removal of the initial cooperative-groups grid.sync body
# speedup vs baseline: 1.0122x; 1.0122x over previous
.LBB0_15:
	v_readlane_b32 s0, v255, 3
	v_readlane_b32 s1, v255, 4
	s_barrier
	s_load_dwordx2 s[0:1], s[0:1], 0x118
	s_waitcnt lgkmcnt(0)
	s_lshl_b32 s3, s0, 1
	s_lshl_b32 s36, s1, 1
	s_cmp_ge_i32 s3, s36
	s_cbranch_scc0 .LBB0_16
	s_getpc_b64 s[98:99]

.LBB0_354:
	v_ashrrev_i32_e32 v7, 4, v3
	v_add_u32_e32 v10, s0, v7
	v_ashrrev_i32_e32 v11, 31, v10
	v_lshlrev_b64 v[10:11], 2, v[10:11]
	v_lshl_add_u64 v[12:13], s[10:11], 0, v[10:11]
	v_lshl_add_u64 v[10:11], s[20:21], 0, v[10:11]
	global_load_dword v9, v[12:13], off
	v_lshl_add_u32 v7, v7, 2, 0
	global_load_dword v12, v[10:11], off
	v_lshl_add_u64 v[10:11], s[6:7], 0, v[4:5]
	global_load_dword v48, v[10:11], off
	v_lshl_add_u64 v[10:11], s[8:9], 0, v[4:5]
	global_load_dword v49, v[10:11], off
	v_lshl_add_u64 v[10:11], s[12:13], 0, v[4:5]
	global_load_dword v50, v[10:11], off
	v_lshl_add_u64 v[10:11], s[14:15], 0, v[4:5]
	global_load_dword v51, v[10:11], off
	ds_read2st64_b32 v[10:11], v7 offset0:1 offset1:34
	s_waitcnt lgkmcnt(0)
	v_add_f32_e32 v7, -1.0, v10
	s_waitcnt vmcnt(4)
	v_mul_f32_e32 v10, v12, v12
	v_mul_f32_e32 v13, v12, v11
	v_fmac_f32_e32 v10, v9, v9
	v_fmac_f32_e32 v13, v9, v7
	v_div_scale_f32 v14, s[18:19], v10, v10, v13
	v_rcp_f32_e32 v15, v14
	v_mul_f32_e32 v7, v12, v7
	v_fma_f32 v7, v9, v11, -v7
	v_div_scale_f32 v9, s[18:19], v10, v10, v7
	v_fma_f32 v16, -v14, v15, 1.0
	v_fmac_f32_e32 v15, v16, v15
	v_div_scale_f32 v16, vcc, v13, v10, v13
	v_rcp_f32_e32 v11, v9
	v_mul_f32_e32 v17, v16, v15
	v_fma_f32 v18, -v14, v17, v16
	v_fmac_f32_e32 v17, v18, v15
	v_fma_f32 v14, -v14, v17, v16
	v_fma_f32 v12, -v9, v11, 1.0
	v_div_fmas_f32 v14, v14, v15, v17
	v_fmac_f32_e32 v11, v12, v11
	v_div_scale_f32 v12, vcc, v7, v10, v7
	v_div_fixup_f32 v13, v14, v10, v13
	v_mul_f32_e32 v14, v12, v11
	v_fma_f32 v15, -v9, v14, v12
	v_fmac_f32_e32 v14, v15, v11
	v_fma_f32 v9, -v9, v14, v12
	v_div_fmas_f32 v9, v9, v11, v14
	v_div_fixup_f32 v7, v9, v10, v7
	s_add_u32 s6, s6, 0x800
	s_addc_u32 s7, s7, 0
	s_add_u32 s8, s8, 0x800
	s_addc_u32 s9, s9, 0
	v_cmp_lt_i32_e32 vcc, s77, v3
	s_waitcnt vmcnt(2)
	v_mul_f32_e32 v11, v49, v7
	v_mul_f32_e32 v7, v48, v7
	v_fma_f32 v11, v48, v13, -v11
	v_fmac_f32_e32 v7, v49, v13
	ds_write2st64_b32 v6, v11, v7 offset1:16
	s_add_u32 s12, s12, 0x800
	s_addc_u32 s13, s13, 0
	s_add_u32 s14, s14, 0x800
	s_addc_u32 s15, s15, 0
	s_or_b64 s[16:17], vcc, s[16:17]
	s_waitcnt vmcnt(0)
	ds_write2st64_b32 v6, v50, v51 offset0:32 offset1:48
	v_add_u32_e32 v7, 0x200, v3
	v_add_u32_e32 v6, 0x800, v6
	v_mov_b32_e32 v3, v7
	s_andn2_b64 exec, exec, s[16:17]
	s_cbranch_execnz .LBB0_354

.LBB0_368:
	s_andn2_saveexec_b64 s[8:9], s[8:9]
	s_cbranch_execz .LBB0_363
	v_ashrrev_i32_e32 v7, 10, v3
	v_cmp_ge_i32_e32 vcc, v7, v9
	v_sub_u32_e32 v7, v7, v9
	v_lshlrev_b32_e32 v11, 6, v6
	v_lshl_add_u32 v7, v7, 10, 0
	v_and_b32_e32 v11, 0x3c0, v11
	v_lshlrev_b32_e32 v12, 2, v18
	v_add3_u32 v18, v7, v11, v12
	v_mov_b32_e32 v52, 0
	v_mov_b32_e32 v53, 0
	v_mov_b32_e32 v54, 0
	v_mov_b32_e32 v55, 0
	v_mov_b32_e32 v56, 0
	v_mov_b32_e32 v57, 0
	v_mov_b32_e32 v58, 0
	v_mov_b32_e32 v59, 0
	s_and_saveexec_b64 s[10:11], vcc
	ds_read_b128 v[52:55], v18 offset:33280
	ds_read_b128 v[56:59], v18 offset:33296
	s_or_b64 exec, exec, s[10:11]
	s_waitcnt lgkmcnt(0)
	v_mov_b32_e32 v11, v52
	v_mov_b32_e32 v7, v53
	v_mov_b32_e32 v13, v54
	v_mov_b32_e32 v12, v55
	v_mov_b32_e32 v15, v56
	v_mov_b32_e32 v14, v57
	v_mov_b32_e32 v16, v58
	v_mov_b32_e32 v17, v59
	s_branch .LBB0_363

.LBB0_725:
	s_andn2_saveexec_b64 s[8:9], s[8:9]
	s_cbranch_execz .LBB0_720
	v_ashrrev_i32_e32 v7, 10, v3
	v_cmp_ge_i32_e32 vcc, v7, v8
	v_sub_u32_e32 v7, v7, v8
	v_lshlrev_b32_e32 v11, 6, v6
	v_lshl_add_u32 v7, v7, 10, 0
	v_and_b32_e32 v11, 0x3c0, v11
	v_lshlrev_b32_e32 v13, 2, v19
	v_add3_u32 v19, v7, v11, v13
	v_mov_b32_e32 v52, 0
	v_mov_b32_e32 v53, 0
	v_mov_b32_e32 v54, 0
	v_mov_b32_e32 v55, 0
	v_mov_b32_e32 v56, 0
	v_mov_b32_e32 v57, 0
	v_mov_b32_e32 v58, 0
	v_mov_b32_e32 v59, 0
	s_and_saveexec_b64 s[12:13], vcc
	ds_read_b128 v[52:55], v19 offset:33280
	ds_read_b128 v[56:59], v19 offset:33296
	s_or_b64 exec, exec, s[12:13]
	s_waitcnt lgkmcnt(0)
	v_mov_b32_e32 v11, v52
	v_mov_b32_e32 v7, v53
	v_mov_b32_e32 v14, v54
	v_mov_b32_e32 v13, v55
	v_mov_b32_e32 v16, v56
	v_mov_b32_e32 v15, v57
	v_mov_b32_e32 v17, v58
	v_mov_b32_e32 v18, v59
	s_branch .LBB0_720
